# same as the previous version but EpiProj keeps the compiler's 16-row x 64-B stores on the adjacent-halves column permutation (no DPP exchange)
# speedup vs baseline: 1.0002x; 1.0002x over previous
.LBB0_933:
	s_waitcnt lgkmcnt(0)
	s_barrier
	ds_read_b32 v158, v156
	v_lshl_or_b32 v150, s12, 8, v153
	v_add_u32_e32 v159, s5, v137
	v_ashrrev_i32_e32 v151, 31, v150
	v_mov_b64_e32 v[148:149], s[94:95]
	v_mad_i64_i32 v[160:161], s[12:13], v159, s34, v[148:149]
	v_lshlrev_b64 v[150:151], 1, v[150:151]
	v_lshl_add_u64 v[160:161], v[160:161], 0, v[150:151]
	s_waitcnt lgkmcnt(0)
	v_pk_mul_f32 v[130:131], v[130:131], v[158:159] op_sel_hi:[1,0]
	v_pk_mul_f32 v[128:129], v[128:129], v[158:159] op_sel_hi:[1,0]
	v_pk_mul_f32 v[162:163], v[126:127], v[158:159] op_sel_hi:[1,0]
	v_pk_mul_f32 v[126:127], v[124:125], v[158:159] op_sel_hi:[1,0]
	v_cvt_pk_bf16_f32 v124, v128, v129
	v_cvt_pk_bf16_f32 v125, v130, v131
	v_pk_mul_f32 v[120:121], v[120:121], v[158:159] op_sel_hi:[1,0]
	v_cvt_pk_bf16_f32 v126, v126, v127
	v_cvt_pk_bf16_f32 v127, v162, v163
	global_store_dwordx4 v[160:161], v[124:127], off
	v_pk_mul_f32 v[122:123], v[122:123], v[158:159] op_sel_hi:[1,0]
	s_andn2_b64 vcc, exec, s[38:39]
	v_pk_mul_f32 v[124:125], v[114:115], v[158:159] op_sel_hi:[1,0]
	v_pk_mul_f32 v[114:115], v[112:113], v[158:159] op_sel_hi:[1,0]
	v_cvt_pk_bf16_f32 v112, v120, v121
	v_cvt_pk_bf16_f32 v113, v122, v123
	s_mov_b64 s[16:17], -1
	v_cvt_pk_bf16_f32 v114, v114, v115
	v_cvt_pk_bf16_f32 v115, v124, v125
	global_store_dwordx4 v[160:161], v[112:115], off offset:64
	ds_read_b32 v112, v156 offset:64
	s_nop 0
	v_or_b32_e32 v113, 16, v159
	v_mad_i64_i32 v[114:115], s[12:13], v113, s34, v[148:149]
	v_lshl_add_u64 v[114:115], v[114:115], 0, v[150:151]
	s_waitcnt lgkmcnt(0)
	v_pk_mul_f32 v[118:119], v[118:119], v[112:113] op_sel_hi:[1,0]
	v_pk_mul_f32 v[116:117], v[116:117], v[112:113] op_sel_hi:[1,0]
	v_pk_mul_f32 v[120:121], v[110:111], v[112:113] op_sel_hi:[1,0]
	v_pk_mul_f32 v[110:111], v[108:109], v[112:113] op_sel_hi:[1,0]
	v_cvt_pk_bf16_f32 v108, v116, v117
	v_cvt_pk_bf16_f32 v109, v118, v119
	v_pk_mul_f32 v[104:105], v[104:105], v[112:113] op_sel_hi:[1,0]
	v_cvt_pk_bf16_f32 v110, v110, v111
	v_cvt_pk_bf16_f32 v111, v120, v121
	global_store_dwordx4 v[114:115], v[108:111], off
	v_pk_mul_f32 v[106:107], v[106:107], v[112:113] op_sel_hi:[1,0]
	s_nop 0
	v_pk_mul_f32 v[108:109], v[98:99], v[112:113] op_sel_hi:[1,0]
	v_pk_mul_f32 v[98:99], v[96:97], v[112:113] op_sel_hi:[1,0]
	v_cvt_pk_bf16_f32 v96, v104, v105
	v_cvt_pk_bf16_f32 v97, v106, v107
	s_nop 0
	v_cvt_pk_bf16_f32 v98, v98, v99
	v_cvt_pk_bf16_f32 v99, v108, v109
	global_store_dwordx4 v[114:115], v[96:99], off offset:64
	ds_read_b32 v96, v156 offset:128
	s_nop 0
	v_or_b32_e32 v97, 32, v159
	v_mad_i64_i32 v[98:99], s[12:13], v97, s34, v[148:149]
	v_lshl_add_u64 v[98:99], v[98:99], 0, v[150:151]
	s_waitcnt lgkmcnt(0)
	v_pk_mul_f32 v[102:103], v[102:103], v[96:97] op_sel_hi:[1,0]
	v_pk_mul_f32 v[100:101], v[100:101], v[96:97] op_sel_hi:[1,0]
	v_pk_mul_f32 v[104:105], v[94:95], v[96:97] op_sel_hi:[1,0]
	v_pk_mul_f32 v[94:95], v[92:93], v[96:97] op_sel_hi:[1,0]
	v_cvt_pk_bf16_f32 v92, v100, v101
	v_cvt_pk_bf16_f32 v93, v102, v103
	v_pk_mul_f32 v[88:89], v[88:89], v[96:97] op_sel_hi:[1,0]
	v_cvt_pk_bf16_f32 v94, v94, v95
	v_cvt_pk_bf16_f32 v95, v104, v105
	global_store_dwordx4 v[98:99], v[92:95], off
	v_pk_mul_f32 v[90:91], v[90:91], v[96:97] op_sel_hi:[1,0]
	s_nop 0
	v_pk_mul_f32 v[92:93], v[82:83], v[96:97] op_sel_hi:[1,0]
	v_pk_mul_f32 v[82:83], v[80:81], v[96:97] op_sel_hi:[1,0]
	v_cvt_pk_bf16_f32 v80, v88, v89
	v_cvt_pk_bf16_f32 v81, v90, v91
	s_nop 0
	v_cvt_pk_bf16_f32 v82, v82, v83
	v_cvt_pk_bf16_f32 v83, v92, v93
	global_store_dwordx4 v[98:99], v[80:83], off offset:64
	ds_read_b32 v80, v156 offset:192
	s_nop 0
	v_or_b32_e32 v81, 48, v159
	v_mad_i64_i32 v[82:83], s[12:13], v81, s34, v[148:149]
	v_lshl_add_u64 v[82:83], v[82:83], 0, v[150:151]
	s_waitcnt lgkmcnt(0)
	v_pk_mul_f32 v[86:87], v[86:87], v[80:81] op_sel_hi:[1,0]
	v_pk_mul_f32 v[84:85], v[84:85], v[80:81] op_sel_hi:[1,0]
	v_pk_mul_f32 v[88:89], v[78:79], v[80:81] op_sel_hi:[1,0]
	v_pk_mul_f32 v[78:79], v[76:77], v[80:81] op_sel_hi:[1,0]
	v_cvt_pk_bf16_f32 v76, v84, v85
	v_cvt_pk_bf16_f32 v77, v86, v87
	v_pk_mul_f32 v[72:73], v[72:73], v[80:81] op_sel_hi:[1,0]
	v_cvt_pk_bf16_f32 v78, v78, v79
	v_cvt_pk_bf16_f32 v79, v88, v89
	global_store_dwordx4 v[82:83], v[76:79], off
	v_pk_mul_f32 v[74:75], v[74:75], v[80:81] op_sel_hi:[1,0]
	s_nop 0
	v_pk_mul_f32 v[76:77], v[70:71], v[80:81] op_sel_hi:[1,0]
	v_pk_mul_f32 v[70:71], v[68:69], v[80:81] op_sel_hi:[1,0]
	v_cvt_pk_bf16_f32 v68, v72, v73
	v_cvt_pk_bf16_f32 v69, v74, v75
	s_nop 0
	v_cvt_pk_bf16_f32 v70, v70, v71
	v_cvt_pk_bf16_f32 v71, v76, v77
	global_store_dwordx4 v[82:83], v[68:71], off offset:64
	ds_read_b32 v68, v156 offset:512
	s_nop 0
	v_add_u32_e32 v69, 0x80, v159
	v_mad_i64_i32 v[70:71], s[12:13], v69, s34, v[148:149]
	v_lshl_add_u64 v[70:71], v[70:71], 0, v[150:151]
	s_waitcnt lgkmcnt(0)
	v_pk_mul_f32 v[66:67], v[66:67], v[68:69] op_sel_hi:[1,0]
	v_pk_mul_f32 v[64:65], v[64:65], v[68:69] op_sel_hi:[1,0]
	v_pk_mul_f32 v[72:73], v[62:63], v[68:69] op_sel_hi:[1,0]
	v_pk_mul_f32 v[62:63], v[60:61], v[68:69] op_sel_hi:[1,0]
	v_cvt_pk_bf16_f32 v60, v64, v65
	v_cvt_pk_bf16_f32 v61, v66, v67
	v_pk_mul_f32 v[56:57], v[56:57], v[68:69] op_sel_hi:[1,0]
	v_cvt_pk_bf16_f32 v62, v62, v63
	v_cvt_pk_bf16_f32 v63, v72, v73
	global_store_dwordx4 v[70:71], v[60:63], off
	v_pk_mul_f32 v[58:59], v[58:59], v[68:69] op_sel_hi:[1,0]
	s_nop 0
	v_pk_mul_f32 v[60:61], v[50:51], v[68:69] op_sel_hi:[1,0]
	v_pk_mul_f32 v[50:51], v[48:49], v[68:69] op_sel_hi:[1,0]
	v_cvt_pk_bf16_f32 v48, v56, v57
	v_cvt_pk_bf16_f32 v49, v58, v59
	s_nop 0
	v_cvt_pk_bf16_f32 v50, v50, v51
	v_cvt_pk_bf16_f32 v51, v60, v61
	global_store_dwordx4 v[70:71], v[48:51], off offset:64
	ds_read_b32 v48, v156 offset:576
	s_nop 0
	v_add_u32_e32 v49, 0x90, v159
	v_mad_i64_i32 v[50:51], s[12:13], v49, s34, v[148:149]
	v_lshl_add_u64 v[50:51], v[50:51], 0, v[150:151]
	s_waitcnt lgkmcnt(0)
	v_pk_mul_f32 v[54:55], v[54:55], v[48:49] op_sel_hi:[1,0]
	v_pk_mul_f32 v[52:53], v[52:53], v[48:49] op_sel_hi:[1,0]
	v_pk_mul_f32 v[56:57], v[46:47], v[48:49] op_sel_hi:[1,0]
	v_pk_mul_f32 v[46:47], v[44:45], v[48:49] op_sel_hi:[1,0]
	v_cvt_pk_bf16_f32 v44, v52, v53
	v_cvt_pk_bf16_f32 v45, v54, v55
	v_pk_mul_f32 v[40:41], v[40:41], v[48:49] op_sel_hi:[1,0]
	v_cvt_pk_bf16_f32 v46, v46, v47
	v_cvt_pk_bf16_f32 v47, v56, v57
	global_store_dwordx4 v[50:51], v[44:47], off
	v_pk_mul_f32 v[42:43], v[42:43], v[48:49] op_sel_hi:[1,0]
	s_nop 0
	v_pk_mul_f32 v[44:45], v[34:35], v[48:49] op_sel_hi:[1,0]
	v_pk_mul_f32 v[34:35], v[32:33], v[48:49] op_sel_hi:[1,0]
	v_cvt_pk_bf16_f32 v32, v40, v41
	v_cvt_pk_bf16_f32 v33, v42, v43
	s_nop 0
	v_cvt_pk_bf16_f32 v34, v34, v35
	v_cvt_pk_bf16_f32 v35, v44, v45
	global_store_dwordx4 v[50:51], v[32:35], off offset:64
	ds_read_b32 v32, v156 offset:640
	s_nop 0
	v_add_u32_e32 v33, 0xa0, v159
	v_mad_i64_i32 v[34:35], s[12:13], v33, s34, v[148:149]
	v_lshl_add_u64 v[34:35], v[34:35], 0, v[150:151]
	s_waitcnt lgkmcnt(0)
	v_pk_mul_f32 v[38:39], v[38:39], v[32:33] op_sel_hi:[1,0]
	v_pk_mul_f32 v[36:37], v[36:37], v[32:33] op_sel_hi:[1,0]
	v_pk_mul_f32 v[40:41], v[30:31], v[32:33] op_sel_hi:[1,0]
	v_pk_mul_f32 v[30:31], v[28:29], v[32:33] op_sel_hi:[1,0]
	v_cvt_pk_bf16_f32 v28, v36, v37
	v_cvt_pk_bf16_f32 v29, v38, v39
	v_pk_mul_f32 v[24:25], v[24:25], v[32:33] op_sel_hi:[1,0]
	v_cvt_pk_bf16_f32 v30, v30, v31
	v_cvt_pk_bf16_f32 v31, v40, v41
	global_store_dwordx4 v[34:35], v[28:31], off
	v_pk_mul_f32 v[26:27], v[26:27], v[32:33] op_sel_hi:[1,0]
	s_nop 0
	v_pk_mul_f32 v[28:29], v[18:19], v[32:33] op_sel_hi:[1,0]
	v_pk_mul_f32 v[18:19], v[16:17], v[32:33] op_sel_hi:[1,0]
	v_cvt_pk_bf16_f32 v16, v24, v25
	v_cvt_pk_bf16_f32 v17, v26, v27
	s_nop 0
	v_cvt_pk_bf16_f32 v18, v18, v19
	v_cvt_pk_bf16_f32 v19, v28, v29
	global_store_dwordx4 v[34:35], v[16:19], off offset:64
	ds_read_b32 v16, v156 offset:704
	s_nop 0
	v_add_u32_e32 v17, 0xb0, v159
	v_mad_i64_i32 v[18:19], s[12:13], v17, s34, v[148:149]
	v_lshl_add_u64 v[18:19], v[18:19], 0, v[150:151]
	s_waitcnt lgkmcnt(0)
	v_pk_mul_f32 v[22:23], v[22:23], v[16:17] op_sel_hi:[1,0]
	v_pk_mul_f32 v[20:21], v[20:21], v[16:17] op_sel_hi:[1,0]
	v_pk_mul_f32 v[24:25], v[14:15], v[16:17] op_sel_hi:[1,0]
	v_pk_mul_f32 v[14:15], v[12:13], v[16:17] op_sel_hi:[1,0]
	v_cvt_pk_bf16_f32 v12, v20, v21
	v_cvt_pk_bf16_f32 v13, v22, v23
	v_pk_mul_f32 v[10:11], v[10:11], v[16:17] op_sel_hi:[1,0]
	v_cvt_pk_bf16_f32 v14, v14, v15
	v_cvt_pk_bf16_f32 v15, v24, v25
	global_store_dwordx4 v[18:19], v[12:15], off
	v_pk_mul_f32 v[8:9], v[8:9], v[16:17] op_sel_hi:[1,0]
	s_nop 0
	v_pk_mul_f32 v[12:13], v[6:7], v[16:17] op_sel_hi:[1,0]
	v_pk_mul_f32 v[6:7], v[4:5], v[16:17] op_sel_hi:[1,0]
	v_cvt_pk_bf16_f32 v4, v8, v9
	v_cvt_pk_bf16_f32 v5, v10, v11
	s_nop 0
	v_cvt_pk_bf16_f32 v6, v6, v7
	v_cvt_pk_bf16_f32 v7, v12, v13
	global_store_dwordx4 v[18:19], v[4:7], off offset:64
	s_cbranch_vccnz .LBB0_920
	s_andn2_b64 vcc, exec, s[0:1]
	s_cbranch_vccnz .LBB0_919
	s_barrier
	s_branch .LBB0_919
